# grouped S5 GEMM phases: units of one group placed on blocks of one XCD class (shared operand tiles hit the same L2)
# speedup vs baseline: 1.0305x; 1.0049x over previous
.LBB0_431:
	s_or_b64 exec, exec, s[0:1]
	s_mov_b32 s101, s6
	s_cmpk_gt_i32 s6, 0x7f
	s_cbranch_scc1 .Lgrp_p3_noremap
	s_and_b32 s98, s6, 7
	s_lshl_b32 s98, s98, 4
	s_lshr_b32 s6, s6, 3
	s_add_i32 s6, s6, s98
.Lgrp_p3_noremap:
	s_add_u32 s22, s90, 0x198f0000
	s_addc_u32 s23, s91, 0
	v_mov_b32_e32 v9, v193
	s_waitcnt lgkmcnt(0)
	s_barrier
	s_cmpk_gt_i32 s6, 0x7f
	v_readfirstlane_b32 s10, v9
	s_cbranch_scc1 .LBB0_447
	v_lshlrev_b32_e32 v0, 4, v9
	v_add_u32_e32 v1, 0x2000, v0
	v_ashrrev_i32_e32 v2, 31, v1
	v_lshrrev_b32_e32 v2, 22, v2
	v_add_u32_e32 v2, v1, v2
	v_ashrrev_i32_e32 v8, 10, v2
	v_mul_i32_i24_e32 v2, 0x400, v8
	v_sub_u32_e32 v1, v1, v2
	v_lshrrev_b32_e32 v2, 4, v1
	v_bitop3_b32 v1, v2, v1, 32 bitop3:0x6c
	v_ashrrev_i32_e32 v2, 31, v1
	v_lshrrev_b32_e32 v2, 26, v2
	v_add_u32_e32 v2, v1, v2
	v_lshlrev_b32_e32 v3, 3, v8
	v_ashrrev_i32_e32 v10, 6, v2
	v_and_b32_e32 v3, -16, v3
	v_add_u32_e32 v3, v10, v3
	v_and_b32_e32 v4, 3, v10
	s_mov_b32 s0, 0x3fffe0
	v_lshrrev_b32_e32 v5, 2, v3
	v_lshlrev_b32_e32 v6, 1, v3
	v_and_b32_e32 v2, 0xc0, v2
	v_and_or_b32 v4, v3, s0, v4
	v_and_b32_e32 v5, 4, v5
	v_and_b32_e32 v6, 24, v6
	v_sub_u32_e32 v1, v1, v2
	v_mov_b32_e32 v2, 1
	v_or3_b32 v4, v4, v5, v6
	v_lshlrev_b32_e32 v5, 5, v8
	v_ashrrev_i16_sdwa v1, v2, sext(v1) dst_sel:DWORD dst_unused:UNUSED_PAD src0_sel:DWORD src1_sel:BYTE_0
	v_and_b32_e32 v11, 32, v5
	v_bfe_i32 v12, v1, 0, 16
	s_movk_i32 s13, 0x300
	v_add_u32_e32 v1, v11, v12
	v_mul_lo_u32 v3, v3, s13
	v_lshlrev_b32_e32 v5, 1, v1
	v_add_lshl_u32 v130, v1, v3, 1
	v_bfe_i32 v1, v9, 27, 1
	v_lshrrev_b32_e32 v1, 22, v1
	v_add_u32_e32 v1, v0, v1
	v_and_b32_e32 v1, 0xfffffc00, v1
	v_sub_u32_e32 v0, v0, v1
	v_lshrrev_b32_e32 v1, 4, v0
	v_ashrrev_i32_e32 v3, 31, v9
	v_bitop3_b32 v0, v1, v0, 32 bitop3:0x6c
	v_lshrrev_b32_e32 v3, 26, v3
	v_ashrrev_i32_e32 v1, 31, v0
	v_add_u32_e32 v3, v9, v3
	v_lshrrev_b32_e32 v1, 26, v1
	v_ashrrev_i32_e32 v14, 6, v3
	v_add_u32_e32 v1, v0, v1
	v_lshlrev_b32_e32 v3, 3, v14
	v_ashrrev_i32_e32 v13, 6, v1
	v_and_b32_e32 v3, -16, v3
	s_add_u32 s2, s90, 0x3760000
	v_lshl_add_u32 v128, v4, 10, v5
	v_add_u32_e32 v3, v13, v3
	v_and_b32_e32 v4, 3, v13
	s_addc_u32 s3, s91, 0
	v_and_or_b32 v4, v3, s0, v4
	s_ashr_i32 s0, s6, 31
	s_lshr_b32 s0, s0, 30
	s_add_i32 s0, s6, s0
	s_ashr_i32 s8, s0, 2
	s_lshl_b32 s0, s6, 8
	s_and_b32 s51, s0, 0x300
	s_ashr_i32 s9, s8, 31
	s_lshl_b64 s[0:1], s[8:9], 11
	s_lshl_b32 s5, s51, 1
	s_or_b32 s0, s0, s5
	s_ashr_i32 s4, s10, 6
	v_lshrrev_b32_e32 v5, 2, v3
	v_lshlrev_b32_e32 v6, 1, v3
	v_and_b32_e32 v1, 0xc0, v1
	s_mulk_i32 s1, 0x300
	s_mul_hi_u32 s5, s0, 0x300
	s_ashr_i32 s11, s10, 8
	s_lshl_b32 s12, s4, 10
	v_and_b32_e32 v5, 4, v5
	v_and_b32_e32 v6, 24, v6
	v_sub_u32_e32 v0, v0, v1
	s_add_i32 s5, s5, s1
	s_mulk_i32 s0, 0x300
	v_or3_b32 v4, v4, v5, v6
	v_lshlrev_b32_e32 v5, 5, v14
	v_ashrrev_i16_sdwa v0, v2, sext(v0) dst_sel:DWORD dst_unused:UNUSED_PAD src0_sel:DWORD src1_sel:BYTE_0
	s_add_u32 s38, s26, s0
	v_and_b32_e32 v15, 32, v5
	v_bfe_i32 v16, v0, 0, 16
	s_addc_u32 s39, s27, s5
	s_lshl_b64 s[0:1], s[8:9], 18
	v_add_u32_e32 v0, v15, v16
	s_add_u32 s40, s2, s0
	v_lshlrev_b32_e32 v1, 1, v0
	s_addc_u32 s41, s3, s1
	s_add_i32 s7, s12, 0
	v_lshl_add_u32 v132, v4, 10, v1
	s_add_i32 m0, s7, 0x10000
	v_mul_lo_u32 v1, v3, s13
	global_load_lds_dwordx4 v132, s[40:41]
	s_add_i32 m0, s7, 0x12000
	s_add_u32 s0, s40, 0x20000
	global_load_lds_dwordx4 v128, s[40:41]
	s_addc_u32 s1, s41, 0
	s_add_i32 m0, s7, 0x14000
	s_add_i32 s33, s7, 0x2000
	global_load_lds_dwordx4 v132, s[0:1]
	s_add_i32 m0, s7, 0x16000
	v_add_lshl_u32 v134, v0, v1, 1
	global_load_lds_dwordx4 v128, s[0:1]
	s_mov_b32 m0, s7
	s_add_u32 s0, s38, 0x30000
	global_load_lds_dwordx4 v134, s[38:39]
	s_mov_b32 m0, s33
	s_addc_u32 s1, s39, 0
	s_add_i32 s34, s7, 0x4000
	global_load_lds_dwordx4 v130, s[38:39]
	s_mov_b32 m0, s34
	s_add_i32 s35, s7, 0x6000
	global_load_lds_dwordx4 v134, s[0:1]
	s_mov_b32 m0, s35
	v_mov_b32_e32 v137, 0
	global_load_lds_dwordx4 v130, s[0:1]
	v_mov_b32_e32 v133, v137
	v_mov_b32_e32 v129, v137
	v_mov_b32_e32 v135, v137
	v_mov_b32_e32 v131, v137
	s_cmp_eq_u32 s11, 1
	s_mov_b32 s48, 0
	v_lshl_add_u64 v[6:7], s[40:41], 0, v[132:133]
	v_lshl_add_u64 v[4:5], s[40:41], 0, v[128:129]
	v_lshl_add_u64 v[0:1], s[38:39], 0, v[134:135]
	s_cselect_b64 s[0:1], -1, 0
	s_cmp_lg_u32 s11, 1
	v_lshl_add_u64 v[2:3], s[38:39], 0, v[130:131]
	s_cbranch_scc1 .LBB0_434
	s_barrier

.LBB0_447:
	s_mov_b32 s6, s101
	v_mov_b32_e32 v150, v193
	s_cmpk_lt_i32 s6, 0x200
	s_cselect_b64 s[28:29], -1, 0
	v_readfirstlane_b32 s0, v150
	s_cmpk_gt_i32 s6, 0x1ff
	s_movk_i32 s2, 0x1ff
	s_cbranch_scc1 .LBB0_492
	v_lshlrev_b32_e32 v0, 3, v150
	v_ashrrev_i32_e32 v1, 31, v0
	v_and_b32_e32 v4, 15, v150
	v_lshl_add_u64 v[2:3], v[0:1], 1, s[90:91]
	v_lshlrev_b32_e32 v1, 2, v150
	v_and_b32_e32 v0, 0xff8, v0
	s_add_i32 s7, 0, 0x10100
	s_ashr_i32 s3, s0, 6
	s_mov_b64 s[0:1], 0x40f0000
	s_movk_i32 s4, 0x7fc
	v_and_b32_e32 v1, 0x7fc, v1
	v_add_u32_e32 v151, s7, v0
	v_add_u32_e32 v0, 7, v4
	v_lshl_add_u64 v[138:139], v[2:3], 0, s[0:1]
	v_lshlrev_b32_e32 v140, 1, v1
	v_cmp_ne_u32_e64 s[0:1], 0, v1
	v_cmp_ne_u32_e64 s[16:17], s4, v1
	v_and_b32_e32 v1, 24, v0
	v_lshlrev_b32_e32 v0, 1, v0
	v_and_b32_e32 v6, 63, v150
	v_and_b32_e32 v0, 48, v0
	v_sub_u32_e32 v0, v6, v0
	v_sub_u32_e32 v1, v1, v4
	v_and_b32_e32 v0, -16, v0
	s_movk_i32 s8, 0x2020
	v_bfe_u32 v7, v150, 4, 2
	s_movk_i32 s64, 0x1010
	v_mad_i32_i24 v10, v1, s8, v0
	v_mov_b32_e32 v0, s7
	v_mad_u32_u24 v153, v4, s64, v0
	v_lshlrev_b32_e32 v0, 2, v7
	v_mov_b32_e32 v141, 0
	v_lshl_or_b32 v0, s3, 8, v0
	v_lshl_add_u64 v[142:143], s[20:21], 0, v[140:141]
	v_lshlrev_b32_e32 v140, 12, v4
	v_ashrrev_i32_e32 v1, 31, v0
	v_cmp_gt_u32_e64 s[4:5], s2, v193
	s_lshl_b32 s2, s3, 9
	v_mul_u32_u24_e32 v9, 0x1010, v4
	v_lshl_add_u64 v[2:3], s[20:21], 0, v[140:141]
	v_lshlrev_b64 v[4:5], 1, v[0:1]
	v_cmp_lt_i32_e32 vcc, 0, v0
	s_movk_i32 s3, 0x70c
	v_add_u32_e32 v1, 48, v150
	v_lshl_add_u64 v[144:145], v[2:3], 0, v[4:5]
	v_cndmask_b32_e64 v146, 0, -1, vcc
	v_cmp_gt_i32_e32 vcc, s3, v0
	v_and_b32_e32 v3, 63, v1
	v_add_u32_e32 v1, 16, v150
	s_movk_i32 s3, 0x70b
	v_cmp_eq_u32_e64 s[8:9], 0, v0
	v_cmp_eq_u32_e64 s[10:11], 3, v7
	v_cmp_gt_u32_e64 s[12:13], 16, v6
	v_and_b32_e32 v6, 63, v1
	v_cmp_lt_i32_e64 s[14:15], s3, v0
	v_lshlrev_b32_e32 v7, 1, v0
	v_lshl_add_u64 v[0:1], s[18:19], 0, v[140:141]
	v_lshl_add_u64 v[148:149], v[0:1], 0, v[4:5]
	v_subrev_u32_e32 v0, s2, v10
	v_add_u32_e32 v0, 0, v0
	v_add_u32_e32 v154, 0x1020, v0
	v_mbcnt_hi_u32_b32 v0, -1, v226
	v_and_b32_e32 v0, 64, v0
	v_lshlrev_b32_e32 v8, 4, v193
	v_and_b32_e32 v152, 48, v150
	v_add_u32_e32 v11, 0, v10
	s_sub_i32 s33, 0, s2
	v_cndmask_b32_e64 v2, 3, 4, vcc
	v_or_b32_e32 v1, v0, v3
	v_or_b32_e32 v0, v0, v6
	v_mov_b32_e32 v147, v146
	v_add3_u32 v155, v9, v152, 0
	v_mov_b32_e32 v156, 0x1000
	v_mov_b32_e32 v157, 0x3000
	s_mov_b32 s65, 0x1000706
	v_mov_b32_e32 v158, 0x2000
	v_lshlrev_b32_e32 v140, 1, v2
	v_mov_b32_e32 v159, 0x4000
	s_mov_b64 s[38:39], 0x4000000
	v_add_u32_e32 v160, 0, v8
	v_add_u32_e32 v161, s33, v11
	v_lshlrev_b32_e32 v162, 2, v1
	v_lshlrev_b32_e32 v163, 2, v0
	v_add_u32_e32 v164, v153, v7
	s_mov_b32 s40, s6

.LBB0_641:
	s_or_b64 exec, exec, s[0:1]
	s_mov_b32 s101, s6
	s_and_b32 s98, s6, 7
	s_lshl_b32 s98, s98, 5
	s_lshr_b32 s6, s6, 3
	s_add_i32 s6, s6, s98
	v_mov_b32_e32 v9, v193
	s_cmpk_lt_i32 s6, 0x100
	s_waitcnt lgkmcnt(0)
	s_barrier
	s_cselect_b64 s[0:1], -1, 0
	s_cmpk_gt_i32 s6, 0xff
	v_readfirstlane_b32 s3, v9
	s_cbranch_scc1 .LBB0_657
	v_lshlrev_b32_e32 v0, 4, v9
	v_add_u32_e32 v1, 0x2000, v0
	v_ashrrev_i32_e32 v2, 31, v1
	v_lshrrev_b32_e32 v2, 22, v2
	v_add_u32_e32 v2, v1, v2
	v_ashrrev_i32_e32 v8, 10, v2
	v_mul_i32_i24_e32 v2, 0x400, v8
	v_sub_u32_e32 v1, v1, v2
	v_lshrrev_b32_e32 v2, 4, v1
	v_bitop3_b32 v1, v2, v1, 32 bitop3:0x6c
	v_ashrrev_i32_e32 v2, 31, v1
	v_lshrrev_b32_e32 v2, 26, v2
	v_add_u32_e32 v2, v1, v2
	v_lshlrev_b32_e32 v3, 3, v8
	v_ashrrev_i32_e32 v10, 6, v2
	v_and_b32_e32 v3, -16, v3
	v_add_u32_e32 v3, v10, v3
	v_and_b32_e32 v4, 3, v10
	s_mov_b32 s2, 0xffffe0
	v_lshrrev_b32_e32 v5, 2, v3
	v_lshlrev_b32_e32 v6, 1, v3
	v_and_b32_e32 v2, 0xc0, v2
	v_and_or_b32 v4, v3, s2, v4
	v_and_b32_e32 v5, 4, v5
	v_and_b32_e32 v6, 24, v6
	v_sub_u32_e32 v1, v1, v2
	v_mov_b32_e32 v2, 1
	v_or3_b32 v4, v4, v5, v6
	v_lshlrev_b32_e32 v5, 5, v8
	v_ashrrev_i16_sdwa v1, v2, sext(v1) dst_sel:DWORD dst_unused:UNUSED_PAD src0_sel:DWORD src1_sel:BYTE_0
	s_movk_i32 s33, 0x300
	v_and_b32_e32 v11, 32, v5
	v_bfe_i32 v12, v1, 0, 16
	v_mul_u32_u24_e32 v4, 0x300, v4
	v_add_u32_e32 v1, v11, v12
	v_mul_lo_u32 v3, v3, s33
	v_add_lshl_u32 v128, v4, v1, 1
	v_add_lshl_u32 v130, v1, v3, 1
	v_bfe_i32 v1, v9, 27, 1
	v_lshrrev_b32_e32 v1, 22, v1
	v_add_u32_e32 v1, v0, v1
	v_and_b32_e32 v1, 0xfffffc00, v1
	v_sub_u32_e32 v0, v0, v1
	v_lshrrev_b32_e32 v1, 4, v0
	v_ashrrev_i32_e32 v3, 31, v9
	v_bitop3_b32 v0, v1, v0, 32 bitop3:0x6c
	v_lshrrev_b32_e32 v3, 26, v3
	v_ashrrev_i32_e32 v1, 31, v0
	v_add_u32_e32 v3, v9, v3
	v_lshrrev_b32_e32 v1, 26, v1
	v_ashrrev_i32_e32 v14, 6, v3
	v_add_u32_e32 v1, v0, v1
	v_lshlrev_b32_e32 v3, 3, v14
	s_add_u32 s66, s90, 0x1f60000
	v_ashrrev_i32_e32 v13, 6, v1
	v_and_b32_e32 v3, -16, v3
	s_addc_u32 s67, s91, 0
	v_add_u32_e32 v3, v13, v3
	v_and_b32_e32 v4, 3, v13
	s_ashr_i32 s9, s6, 31
	v_and_or_b32 v4, v3, s2, v4
	s_lshr_b32 s2, s6, 31
	s_lshr_b32 s9, s9, 29
	s_add_i32 s2, s6, s2
	s_add_i32 s9, s6, s9
	s_and_b32 s8, s2, 0xfffffe
	s_ashr_i32 s54, s9, 3
	s_lshl_b32 s2, s2, 7
	s_sub_i32 s8, s6, s8
	s_and_b32 s2, s2, 0x300
	s_ashr_i32 s55, s54, 31
	s_lshl_b32 s56, s8, 8
	s_lshl_b64 s[8:9], s[54:55], 11
	s_lshl_b32 s11, s2, 1
	s_or_b32 s8, s8, s11
	s_ashr_i32 s10, s3, 6
	s_mulk_i32 s9, 0x300
	s_mul_hi_u32 s11, s8, 0x300
	s_ashr_i32 s7, s3, 8
	s_lshl_b32 s68, s10, 10
	s_add_i32 s11, s11, s9
	s_mulk_i32 s8, 0x300
	s_add_u32 s58, s26, s8
	s_addc_u32 s59, s27, s11
	s_ashr_i32 s57, s56, 31
	s_lshl_b64 s[8:9], s[54:55], 10
	s_lshl_b64 s[30:31], s[56:57], 1
	s_add_u32 s8, s30, s8
	v_lshrrev_b32_e32 v5, 2, v3
	v_lshlrev_b32_e32 v6, 1, v3
	v_and_b32_e32 v1, 0xc0, v1
	s_addc_u32 s9, s31, s9
	v_and_b32_e32 v5, 4, v5
	v_and_b32_e32 v6, 24, v6
	v_sub_u32_e32 v0, v0, v1
	s_mulk_i32 s9, 0x300
	s_mul_hi_u32 s11, s8, 0x300
	v_or3_b32 v4, v4, v5, v6
	v_lshlrev_b32_e32 v5, 5, v14
	v_ashrrev_i16_sdwa v0, v2, sext(v0) dst_sel:DWORD dst_unused:UNUSED_PAD src0_sel:DWORD src1_sel:BYTE_0
	s_add_i32 s11, s11, s9
	s_mulk_i32 s8, 0x300
	v_and_b32_e32 v15, 32, v5
	v_bfe_i32 v16, v0, 0, 16
	s_add_u32 s60, s66, s8
	v_mul_u32_u24_e32 v4, 0x300, v4
	v_add_u32_e32 v0, v15, v16
	s_addc_u32 s61, s67, s11
	s_add_i32 s57, s68, 0
	v_add_lshl_u32 v132, v4, v0, 1
	s_add_i32 m0, s57, 0x10000
	v_mul_lo_u32 v1, v3, s33
	global_load_lds_dwordx4 v132, s[60:61]
	s_add_i32 m0, s57, 0x12000
	s_add_u32 s8, s60, 0x30000
	global_load_lds_dwordx4 v128, s[60:61]
	s_addc_u32 s9, s61, 0
	s_add_i32 m0, s57, 0x14000
	s_add_i32 s69, s57, 0x2000
	global_load_lds_dwordx4 v132, s[8:9]
	s_add_i32 m0, s57, 0x16000
	v_add_lshl_u32 v134, v0, v1, 1
	global_load_lds_dwordx4 v128, s[8:9]
	s_mov_b32 m0, s57
	s_add_u32 s8, s58, 0x30000
	global_load_lds_dwordx4 v134, s[58:59]
	s_mov_b32 m0, s69
	s_addc_u32 s9, s59, 0
	s_add_i32 s70, s57, 0x4000
	global_load_lds_dwordx4 v130, s[58:59]
	s_mov_b32 m0, s70
	s_add_i32 s71, s57, 0x6000
	global_load_lds_dwordx4 v134, s[8:9]
	s_mov_b32 m0, s71
	v_mov_b32_e32 v137, 0
	global_load_lds_dwordx4 v130, s[8:9]
	v_mov_b32_e32 v133, v137
	v_mov_b32_e32 v129, v137
	v_mov_b32_e32 v135, v137
	v_mov_b32_e32 v131, v137
	s_cmp_eq_u32 s7, 1
	s_mov_b32 s72, 0
	v_lshl_add_u64 v[6:7], s[60:61], 0, v[132:133]
	v_lshl_add_u64 v[4:5], s[60:61], 0, v[128:129]
	v_lshl_add_u64 v[0:1], s[58:59], 0, v[134:135]
	s_cselect_b64 s[8:9], -1, 0
	s_cmp_lg_u32 s7, 1
	v_lshl_add_u64 v[2:3], s[58:59], 0, v[130:131]
	s_cbranch_scc1 .LBB0_644
	s_barrier

.LBB0_657:
	s_mov_b32 s6, s101
	s_waitcnt vmcnt(0)
	s_waitcnt vmcnt(0)
	s_barrier
	s_and_saveexec_b64 s[8:9], s[80:81]
	s_cbranch_execz .LBB0_709
	v_readlane_b32 s98, v248, 1
	v_readlane_b32 s99, v248, 2
	v_mov_b32_e32 v0, 0x20ff0
	ds_read2_b32 v[2:3], v0 offset1:1
	v_mov_b32_e32 v1, 1
	v_mov_b32_e32 v4, s97
	v_lshlrev_b32_e32 v4, 8, v4
	s_add_u32 s98, s98, 0x1000
	s_addc_u32 s99, s99, 0
	s_nop 2
	global_atomic_add v5, v4, v1, s[98:99] offset:1024 sc0
	s_waitcnt vmcnt(0) lgkmcnt(0)
	v_mul_u32_u24_e32 v2, 6, v2
	v_mul_u32_u24_e32 v3, 6, v3
	v_add_u32_e32 v5, 1, v5
	v_cmp_ne_u32_e32 vcc, v5, v2
	v_mov_b32_e32 v6, 0x2400
	s_cbranch_vccnz .Lxb5_poll
	buffer_wbl2 sc1
	s_waitcnt vmcnt(0)
	global_atomic_add v6, v1, s[98:99]
